# weight-conversion schedule: 3072 items moved from the L0 gate/up bubble (84 workgroups) into the L0 input-GEMM pool (all workgroups), N7/N6 = 158/238
# baseline (speedup 1.0000x reference)
.LBB0_119:
	s_or_b64 exec, exec, s[0:1]
	v_mov_b32_e32 v157, v183
	s_waitcnt lgkmcnt(0)
	s_barrier
	s_mov_b64 s[14:15], s[70:71]
	v_readfirstlane_b32 s2, v157
	s_cmpk_gt_i32 s20, 0x71
	s_cbranch_scc0 .LBB0_121
	s_mul_i32 s0, s20, 0xee
	s_add_i32 s3, s0, 0xffffdc60
	s_movk_i32 s0, 0xee
	s_cbranch_execz .LBB0_122
	s_branch .LBB0_123
.LBB0_121:
	s_movk_i32 s0, 0xee
.LBB0_122:
	s_movk_i32 s0, 0x9e
	s_mul_i32 s3, s20, 0x9e
.LBB0_123:
	s_ashr_i32 s72, s2, 6
	s_add_u32 s30, s14, 0x100000
	s_addc_u32 s31, s15, 0
	s_add_i32 s73, s3, 0x3200
	s_add_i32 s0, s73, s0
	s_cmpk_lg_i32 s20, 0xff
	s_cselect_b32 s33, s0, 0xfc80
	s_bitcmp0_b32 s20, 0
	s_cselect_b64 s[74:75], -1, 0
	s_and_b64 s[0:1], s[74:75], s[82:83]
	s_andn2_b64 vcc, exec, s[0:1]
	v_and_b32_e32 v155, 63, v157
	s_cbranch_vccnz .LBB0_174
	s_add_i32 s21, s73, s72
	s_cmp_ge_i32 s21, s33
	s_cbranch_scc1 .LBB0_173
	s_mul_hi_i32 s0, s21, 0x78787879
	s_lshr_b32 s1, s0, 31
	s_ashr_i32 s0, s0, 14
	s_add_i32 s2, s0, s1
	s_mul_i32 s0, s2, 0x8800
	s_sub_i32 s24, s21, s0
	s_ashr_i32 s3, s2, 31
	s_mul_i32 s0, s2, 0x8800000
	s_mul_hi_i32 s1, s2, 0x8800000
	s_add_u32 s0, s30, s0
	s_addc_u32 s1, s31, s1
	s_cmpk_gt_i32 s24, 0x31ff
	s_cbranch_scc0 .LBB0_130
	s_cmpk_gt_u32 s24, 0x3dff
	s_cbranch_scc0 .LBB0_131
	s_cmpk_gt_u32 s24, 0x45ff
	s_cbranch_scc0 .LBB0_134
	s_cmpk_gt_u32 s24, 0x71ff
	s_cbranch_scc0 .LBB0_135
	s_add_i32 s4, s24, 0xffff8e00
	v_readlane_b32 s36, v254, 0
	s_lshr_b32 s5, s4, 6
	s_mul_i32 s6, s2, 0x2c00000
	v_readlane_b32 s42, v254, 6
	s_mul_hi_i32 s4, s2, 0x2c00000
	v_readlane_b32 s43, v254, 7
	s_add_u32 s6, s42, s6
	s_addc_u32 s7, s43, s4
	s_lshl_b32 s4, s24, 5
	s_and_b32 s4, s4, 0x7e0
	s_add_u32 s10, s0, 0x7200000
	v_readlane_b32 s37, v254, 1
	v_readlane_b32 s38, v254, 2
	v_readlane_b32 s39, v254, 3
	v_readlane_b32 s40, v254, 4
	v_readlane_b32 s41, v254, 5
	s_addc_u32 s11, s1, 0
	s_mov_b64 s[8:9], 0
	s_branch .LBB0_136

.LBB0_919:
	s_cmpk_lt_i32 s20, 0xac
	v_readlane_b32 s4, v255, 0
	s_cselect_b64 s[2:3], -1, 0
	v_readlane_b32 s5, v255, 1
	s_or_b64 s[2:3], s[2:3], s[4:5]
	s_and_b64 vcc, exec, s[2:3]
	s_cbranch_vccnz .LBB0_967
	s_ashr_i32 s5, s21, 6
	v_readlane_b32 s2, v254, 46
	s_add_i32 s2, s2, s5
	s_addk_i32 s2, 0xfaa0
	s_cmpk_gt_i32 s2, 0x137f
	s_cbranch_scc1 .LBB0_967
	s_add_i32 s29, s2, 0xfc80
	s_add_u32 s21, s0, 0x100000
	s_mul_hi_i32 s0, s29, 0x78787879
	s_addc_u32 s28, s1, 0
	s_lshr_b32 s1, s0, 31
	s_ashr_i32 s0, s0, 14
	s_add_i32 s2, s0, s1
	s_mul_i32 s0, s2, 0x8800
	s_sub_i32 s17, s29, s0
	s_ashr_i32 s3, s2, 31
	s_mul_i32 s0, s2, 0x8800000
	s_mul_hi_i32 s1, s2, 0x8800000
	s_add_u32 s0, s21, s0
	s_addc_u32 s1, s28, s1
	s_cmpk_gt_i32 s17, 0x31ff
	s_cbranch_scc0 .LBB0_926
	s_cmpk_gt_u32 s17, 0x3dff
	s_cbranch_scc0 .LBB0_927
	s_cmpk_gt_u32 s17, 0x45ff
	s_cbranch_scc0 .LBB0_928
	s_cmpk_gt_u32 s17, 0x71ff
	s_cbranch_scc0 .LBB0_929
	s_add_i32 s4, s17, 0xffff8e00
	v_readlane_b32 s8, v254, 0
	s_lshr_b32 s16, s4, 6
	s_mul_i32 s6, s2, 0x2c00000
	v_readlane_b32 s14, v254, 6
	s_mul_hi_i32 s4, s2, 0x2c00000
	v_readlane_b32 s15, v254, 7
	s_add_u32 s6, s14, s6
	s_addc_u32 s7, s15, s4
	s_lshl_b32 s4, s17, 5
	v_readlane_b32 s10, v254, 2
	s_and_b32 s4, s4, 0x7e0
	v_readlane_b32 s9, v254, 1
	v_readlane_b32 s11, v254, 3
	s_add_u32 s10, s0, 0x7200000
	v_readlane_b32 s12, v254, 4
	v_readlane_b32 s13, v254, 5
	s_addc_u32 s11, s1, 0
	s_mov_b64 s[8:9], 0
	s_branch .LBB0_930
